# P4 epilogue: gain/bias loads issued before the statistics hand-off (into dead fragment registers) and copied after the barrier
# speedup vs baseline: 1.0278x; 1.0001x over previous
.LBB0_518:
	s_or_b64 exec, exec, s[8:9]
	global_load_dwordx4 v[224:227], v[174:175], off
	global_load_dwordx4 v[228:231], v[172:173], off
	global_load_dwordx4 v[232:235], v[172:173], off offset:64
	global_load_dwordx4 v[236:239], v[174:175], off offset:64
	global_load_dwordx4 v[240:243], v[174:175], off offset:128
	global_load_dwordx4 v[244:247], v[172:173], off offset:128
	global_load_dwordx4 v[248:251], v[172:173], off offset:192
	global_load_dwordx4 v[192:195], v[174:175], off offset:192
	s_and_saveexec_b64 s[46:47], s[4:5]
	s_cbranch_execz .LBB0_529
	v_lshlrev_b64 v[128:129], 6, v[128:129]
	v_lshl_add_u64 v[128:129], s[22:23], 0, v[128:129]
	s_mov_b32 s8, 0
	s_mov_b64 s[50:51], exec
	s_mov_b64 exec, 1

.LBB0_529:
	s_or_b64 exec, exec, s[46:47]
	s_waitcnt lgkmcnt(0)
	s_barrier
	s_waitcnt vmcnt(0)
	v_mov_b64_e32 v[144:145], v[224:225]
	v_mov_b64_e32 v[146:147], v[226:227]
	v_mov_b64_e32 v[156:157], v[228:229]
	v_mov_b64_e32 v[158:159], v[230:231]
	v_mov_b64_e32 v[148:149], v[232:233]
	v_mov_b64_e32 v[150:151], v[234:235]
	v_mov_b64_e32 v[152:153], v[236:237]
	v_mov_b64_e32 v[154:155], v[238:239]
	v_mov_b64_e32 v[128:129], v[240:241]
	v_mov_b64_e32 v[130:131], v[242:243]
	v_mov_b64_e32 v[140:141], v[244:245]
	v_mov_b64_e32 v[142:143], v[246:247]
	v_mov_b64_e32 v[132:133], v[248:249]
	v_mov_b64_e32 v[134:135], v[250:251]
	v_mov_b64_e32 v[136:137], v[192:193]
	v_mov_b64_e32 v[138:139], v[194:195]
	ds_read_b64 v[194:195], v200
	v_mov_b32_e32 v223, v169
	v_mov_b32_e32 v224, v169
	v_mov_b32_e32 v225, v169
	v_mov_b32_e32 v226, v169
	s_waitcnt lgkmcnt(0)
	v_sub_f32_e32 v230, v100, v194
	v_sub_f32_e32 v231, v101, v194
	v_pk_add_f32 v[100:101], v[108:109], v[194:195] op_sel_hi:[1,0] neg_lo:[0,1] neg_hi:[0,1]
	v_sub_f32_e32 v108, v102, v194
	v_sub_f32_e32 v109, v103, v194
	v_pk_add_f32 v[102:103], v[110:111], v[194:195] op_sel_hi:[1,0] neg_lo:[0,1] neg_hi:[0,1]
	v_sub_f32_e32 v110, v92, v194
	v_sub_f32_e32 v111, v93, v194
	v_pk_add_f32 v[92:93], v[96:97], v[194:195] op_sel_hi:[1,0] neg_lo:[0,1] neg_hi:[0,1]
	v_sub_f32_e32 v232, v94, v194
	v_sub_f32_e32 v233, v95, v194
	v_pk_add_f32 v[94:95], v[98:99], v[194:195] op_sel_hi:[1,0] neg_lo:[0,1] neg_hi:[0,1]
	v_mul_f32_e32 v230, v195, v230
	v_mul_f32_e32 v231, v195, v231
	v_pk_mul_f32 v[96:97], v[194:195], v[100:101] op_sel:[1,0]
	v_mul_f32_e32 v100, v195, v108
	v_mul_f32_e32 v101, v195, v109
	v_pk_mul_f32 v[98:99], v[194:195], v[102:103] op_sel:[1,0]
	v_mul_f32_e32 v102, v195, v110
	v_mul_f32_e32 v103, v195, v111
	v_pk_mul_f32 v[92:93], v[194:195], v[92:93] op_sel:[1,0]
	v_mul_f32_e32 v110, v195, v232
	v_mul_f32_e32 v111, v195, v233
	v_pk_mul_f32 v[94:95], v[194:195], v[94:95] op_sel:[1,0]
	v_lshl_add_u64 v[184:185], v[176:177], 0, v[184:185]
	v_lshl_add_u64 v[190:191], v[184:185], 0, v[182:183]
	v_lshl_add_u64 v[192:193], v[184:185], 0, v[168:169]
	ds_read_b64 v[184:185], v202
	ds_read_b64 v[186:187], v204
	ds_read_b64 v[188:189], v206
	v_mov_b32_e32 v227, v169
	v_mov_b32_e32 v228, v169
	v_mov_b32_e32 v229, v169
	s_waitcnt lgkmcnt(2)
	v_sub_f32_e32 v72, v72, v184
	v_mul_f32_e32 v72, v185, v72
	v_sub_f32_e32 v74, v74, v184
	v_mul_f32_e32 v74, v185, v74
	v_sub_f32_e32 v64, v64, v184
	v_mul_f32_e32 v64, v185, v64
	v_sub_f32_e32 v66, v66, v184
	v_mul_f32_e32 v66, v185, v66
	s_andn2_b64 vcc, exec, s[44:45]
	s_mov_b64 s[8:9], -1
	s_waitcnt vmcnt(6)
	v_fma_f32 v194, v156, v230, v144
	v_fma_f32 v195, v157, v231, v145
	s_waitcnt vmcnt(4)
	v_pk_fma_f32 v[96:97], v[148:149], v[96:97], v[152:153]
	v_fma_f32 v100, v158, v100, v146
	v_fma_f32 v101, v159, v101, v147
	v_pk_fma_f32 v[98:99], v[150:151], v[98:99], v[154:155]
	s_waitcnt vmcnt(0)
	v_pk_fma_f32 v[108:109], v[132:133], v[92:93], v[136:137]
	v_fma_f32 v230, v142, v110, v130
	v_fma_f32 v231, v143, v111, v131
	v_pk_fma_f32 v[110:111], v[134:135], v[94:95], v[138:139]
	v_cndmask_b32_e64 v92, v194, v96, s[0:1]
	v_cndmask_b32_e64 v93, v195, v97, s[0:1]
	v_cndmask_b32_e64 v94, v100, v98, s[0:1]
	v_cndmask_b32_e64 v95, v101, v99, s[0:1]
	v_mov_b32_dpp v223, v92 row_ror:8 row_mask:0xf bank_mask:0xf
	v_mov_b32_dpp v224, v93 row_ror:8 row_mask:0xf bank_mask:0xf
	v_mov_b32_dpp v225, v94 row_ror:8 row_mask:0xf bank_mask:0xf
	v_mov_b32_dpp v226, v95 row_ror:8 row_mask:0xf bank_mask:0xf
	v_fma_f32 v102, v140, v102, v128
	v_fma_f32 v103, v141, v103, v129
	v_cndmask_b32_e64 v92, v223, v194, s[0:1]
	v_cndmask_b32_e64 v93, v224, v195, s[0:1]
	v_cndmask_b32_e64 v94, v225, v100, s[0:1]
	v_cndmask_b32_e64 v95, v226, v101, s[0:1]
	v_cndmask_b32_e64 v232, v102, v108, s[0:1]
	v_cndmask_b32_e64 v233, v103, v109, s[0:1]
	v_cndmask_b32_e64 v234, v230, v110, s[0:1]
	v_cndmask_b32_e64 v99, v99, v226, s[0:1]
	v_cndmask_b32_e64 v98, v98, v225, s[0:1]
	v_cndmask_b32_e64 v97, v97, v224, s[0:1]
	v_cndmask_b32_e64 v96, v96, v223, s[0:1]
	global_store_dwordx4 v[190:191], v[92:95], off nt
	global_store_dwordx4 v[192:193], v[96:99], off nt
	v_mov_b32_dpp v227, v232 row_ror:8 row_mask:0xf bank_mask:0xf
	v_cndmask_b32_e64 v92, v231, v111, s[0:1]
	v_mov_b32_e32 v93, v169
	v_mov_b32_dpp v228, v233 row_ror:8 row_mask:0xf bank_mask:0xf
	v_mov_b32_dpp v229, v234 row_ror:8 row_mask:0xf bank_mask:0xf
	v_mov_b32_dpp v93, v92 row_ror:8 row_mask:0xf bank_mask:0xf
	v_cndmask_b32_e64 v100, v227, v102, s[0:1]
	v_cndmask_b32_e64 v101, v228, v103, s[0:1]
	v_cndmask_b32_e64 v102, v229, v230, s[0:1]
	v_cndmask_b32_e64 v103, v93, v231, s[0:1]
	v_cndmask_b32_e64 v94, v110, v229, s[0:1]
	v_cndmask_b32_e64 v95, v111, v93, s[0:1]
	v_cndmask_b32_e64 v93, v109, v228, s[0:1]
	v_cndmask_b32_e64 v92, v108, v227, s[0:1]
	global_store_dwordx4 v[190:191], v[100:103], off offset:128 nt
	global_store_dwordx4 v[192:193], v[92:95], off offset:128 nt
	v_mov_b32_e32 v96, v169
	v_mov_b32_e32 v97, v169
	v_fma_f32 v94, v156, v72, v144
	v_sub_f32_e32 v72, v73, v184
	v_mul_f32_e32 v72, v185, v72
	v_fma_f32 v95, v157, v72, v145
	v_pk_add_f32 v[72:73], v[76:77], v[184:185] op_sel_hi:[1,0] neg_lo:[0,1] neg_hi:[0,1]
	v_add_u32_e32 v92, s48, v201
	v_pk_mul_f32 v[72:73], v[184:185], v[72:73] op_sel:[1,0]
	v_ashrrev_i32_e32 v93, 31, v92
	v_pk_fma_f32 v[76:77], v[148:149], v[72:73], v[152:153]
	v_mov_b32_e32 v98, v169
	v_cndmask_b32_e64 v72, v94, v76, s[0:1]
	v_mov_b32_e32 v99, v169
	v_lshlrev_b64 v[92:93], 13, v[92:93]
	v_mov_b32_dpp v96, v72 row_ror:8 row_mask:0xf bank_mask:0xf
	v_cndmask_b32_e64 v72, v95, v77, s[0:1]
	v_lshl_add_u64 v[92:93], v[176:177], 0, v[92:93]
	v_cndmask_b32_e64 v76, v76, v96, s[0:1]
	v_mov_b32_dpp v97, v72 row_ror:8 row_mask:0xf bank_mask:0xf
	v_cndmask_b32_e64 v72, v96, v94, s[0:1]
	v_fma_f32 v94, v158, v74, v146
	v_sub_f32_e32 v74, v75, v184
	v_mul_f32_e32 v74, v185, v74
	v_cndmask_b32_e64 v73, v97, v95, s[0:1]
	v_fma_f32 v95, v159, v74, v147
	v_pk_add_f32 v[74:75], v[78:79], v[184:185] op_sel_hi:[1,0] neg_lo:[0,1] neg_hi:[0,1]
	v_cndmask_b32_e64 v77, v77, v97, s[0:1]
	v_pk_mul_f32 v[74:75], v[184:185], v[74:75] op_sel:[1,0]
	s_nop 0
	v_pk_fma_f32 v[78:79], v[150:151], v[74:75], v[154:155]
	s_nop 0
	v_cndmask_b32_e64 v74, v94, v78, s[0:1]
	s_nop 1
	v_mov_b32_dpp v98, v74 row_ror:8 row_mask:0xf bank_mask:0xf
	v_cndmask_b32_e64 v74, v95, v79, s[0:1]
	v_cndmask_b32_e64 v78, v78, v98, s[0:1]
	s_nop 0
	v_mov_b32_dpp v99, v74 row_ror:8 row_mask:0xf bank_mask:0xf
	v_cndmask_b32_e64 v74, v98, v94, s[0:1]
	v_cndmask_b32_e64 v75, v99, v95, s[0:1]
	v_lshl_add_u64 v[94:95], v[92:93], 0, v[182:183]
	global_store_dwordx4 v[94:95], v[72:75], off nt
	v_cndmask_b32_e64 v79, v79, v99, s[0:1]
	s_nop 0
	v_fma_f32 v74, v140, v64, v128
	v_sub_f32_e32 v64, v65, v184
	v_mul_f32_e32 v64, v185, v64
	v_fma_f32 v75, v141, v64, v129
	v_pk_add_f32 v[64:65], v[68:69], v[184:185] op_sel_hi:[1,0] neg_lo:[0,1] neg_hi:[0,1]
	v_lshl_add_u64 v[72:73], v[92:93], 0, v[168:169]
	v_pk_mul_f32 v[64:65], v[184:185], v[64:65] op_sel:[1,0]
	global_store_dwordx4 v[72:73], v[76:79], off nt
	v_pk_fma_f32 v[68:69], v[132:133], v[64:65], v[136:137]
	s_nop 0
	v_cndmask_b32_e64 v64, v74, v68, s[0:1]
	v_mov_b32_e32 v76, v169
	v_mov_b32_e32 v77, v169
	v_mov_b32_e32 v78, v169
	v_mov_b32_dpp v76, v64 row_ror:8 row_mask:0xf bank_mask:0xf
	v_cndmask_b32_e64 v64, v75, v69, s[0:1]
	v_mov_b32_e32 v79, v169
	v_cndmask_b32_e64 v68, v68, v76, s[0:1]
	v_mov_b32_dpp v77, v64 row_ror:8 row_mask:0xf bank_mask:0xf
	v_cndmask_b32_e64 v64, v76, v74, s[0:1]
	v_fma_f32 v74, v142, v66, v130
	v_sub_f32_e32 v66, v67, v184
	v_mul_f32_e32 v66, v185, v66
	v_cndmask_b32_e64 v65, v77, v75, s[0:1]
	v_fma_f32 v75, v143, v66, v131
	v_pk_add_f32 v[66:67], v[70:71], v[184:185] op_sel_hi:[1,0] neg_lo:[0,1] neg_hi:[0,1]
	v_cndmask_b32_e64 v69, v69, v77, s[0:1]
	v_pk_mul_f32 v[66:67], v[184:185], v[66:67] op_sel:[1,0]
	s_nop 0
	v_pk_fma_f32 v[70:71], v[134:135], v[66:67], v[138:139]
	s_nop 0
	v_cndmask_b32_e64 v66, v74, v70, s[0:1]
	s_nop 1
	v_mov_b32_dpp v78, v66 row_ror:8 row_mask:0xf bank_mask:0xf
	v_cndmask_b32_e64 v66, v75, v71, s[0:1]
	v_cndmask_b32_e64 v70, v70, v78, s[0:1]
	s_nop 0
	v_mov_b32_dpp v79, v66 row_ror:8 row_mask:0xf bank_mask:0xf
	v_cndmask_b32_e64 v66, v78, v74, s[0:1]
	v_cndmask_b32_e64 v67, v79, v75, s[0:1]
	v_cndmask_b32_e64 v71, v71, v79, s[0:1]
	global_store_dwordx4 v[94:95], v[64:67], off offset:128 nt
	global_store_dwordx4 v[72:73], v[68:71], off offset:128 nt
	v_mov_b32_e32 v74, v169
	s_waitcnt lgkmcnt(1)
	v_sub_f32_e32 v64, v124, v186
	v_mul_f32_e32 v64, v187, v64
	v_fma_f32 v66, v156, v64, v144
	v_sub_f32_e32 v64, v125, v186
	v_mul_f32_e32 v64, v187, v64
	v_fma_f32 v67, v157, v64, v145
	v_pk_add_f32 v[64:65], v[120:121], v[186:187] op_sel_hi:[1,0] neg_lo:[0,1] neg_hi:[0,1]
	v_mov_b32_e32 v75, v169
	v_pk_mul_f32 v[64:65], v[186:187], v[64:65] op_sel:[1,0]
	v_add_u32_e32 v72, s48, v203
	v_pk_fma_f32 v[68:69], v[148:149], v[64:65], v[152:153]
	v_ashrrev_i32_e32 v73, 31, v72
	v_cndmask_b32_e64 v64, v66, v68, s[0:1]
	v_mov_b32_e32 v78, v169
	v_mov_b32_e32 v79, v169
	v_mov_b32_dpp v74, v64 row_ror:8 row_mask:0xf bank_mask:0xf
	v_cndmask_b32_e64 v64, v67, v69, s[0:1]
	v_lshlrev_b64 v[72:73], 13, v[72:73]
	v_lshl_add_u64 v[72:73], v[176:177], 0, v[72:73]
	v_mov_b32_dpp v75, v64 row_ror:8 row_mask:0xf bank_mask:0xf
	v_cndmask_b32_e64 v64, v74, v66, s[0:1]
	v_sub_f32_e32 v66, v126, v186
	v_mul_f32_e32 v66, v187, v66
	v_fma_f32 v76, v158, v66, v146
	v_sub_f32_e32 v66, v127, v186
	v_mul_f32_e32 v66, v187, v66
	v_cndmask_b32_e64 v65, v75, v67, s[0:1]
	v_fma_f32 v77, v159, v66, v147
	v_pk_add_f32 v[66:67], v[122:123], v[186:187] op_sel_hi:[1,0] neg_lo:[0,1] neg_hi:[0,1]
	v_cndmask_b32_e64 v69, v69, v75, s[0:1]
	v_pk_mul_f32 v[66:67], v[186:187], v[66:67] op_sel:[1,0]
	v_cndmask_b32_e64 v68, v68, v74, s[0:1]
	v_pk_fma_f32 v[70:71], v[150:151], v[66:67], v[154:155]
	v_lshl_add_u64 v[74:75], v[72:73], 0, v[182:183]
	v_cndmask_b32_e64 v66, v76, v70, s[0:1]
	v_lshl_add_u64 v[72:73], v[72:73], 0, v[168:169]
	s_nop 0
	v_mov_b32_dpp v78, v66 row_ror:8 row_mask:0xf bank_mask:0xf
	v_cndmask_b32_e64 v66, v77, v71, s[0:1]
	v_cndmask_b32_e64 v70, v70, v78, s[0:1]
	s_nop 0
	v_mov_b32_dpp v79, v66 row_ror:8 row_mask:0xf bank_mask:0xf
	v_cndmask_b32_e64 v66, v78, v76, s[0:1]
	v_cndmask_b32_e64 v67, v79, v77, s[0:1]
	global_store_dwordx4 v[74:75], v[64:67], off nt
	v_cndmask_b32_e64 v71, v71, v79, s[0:1]
	global_store_dwordx4 v[72:73], v[68:71], off nt
	v_sub_f32_e32 v64, v84, v186
	v_mul_f32_e32 v64, v187, v64
	v_fma_f32 v66, v140, v64, v128
	v_sub_f32_e32 v64, v85, v186
	v_mul_f32_e32 v64, v187, v64
	v_fma_f32 v67, v141, v64, v129
	v_pk_add_f32 v[64:65], v[104:105], v[186:187] op_sel_hi:[1,0] neg_lo:[0,1] neg_hi:[0,1]
	v_mov_b32_e32 v76, v169
	v_pk_mul_f32 v[64:65], v[186:187], v[64:65] op_sel:[1,0]
	v_mov_b32_e32 v77, v169
	v_pk_fma_f32 v[68:69], v[132:133], v[64:65], v[136:137]
	v_mov_b32_e32 v84, v169
	v_cndmask_b32_e64 v64, v66, v68, s[0:1]
	v_mov_b32_e32 v85, v169
	s_nop 0
	v_mov_b32_dpp v76, v64 row_ror:8 row_mask:0xf bank_mask:0xf
	v_cndmask_b32_e64 v64, v67, v69, s[0:1]
	v_cndmask_b32_e64 v68, v68, v76, s[0:1]
	s_nop 0
	v_mov_b32_dpp v77, v64 row_ror:8 row_mask:0xf bank_mask:0xf
	v_cndmask_b32_e64 v64, v76, v66, s[0:1]
	v_sub_f32_e32 v66, v86, v186
	v_mul_f32_e32 v66, v187, v66
	v_fma_f32 v78, v142, v66, v130
	v_sub_f32_e32 v66, v87, v186
	v_mul_f32_e32 v66, v187, v66
	v_cndmask_b32_e64 v65, v77, v67, s[0:1]
	v_fma_f32 v79, v143, v66, v131
	v_pk_add_f32 v[66:67], v[106:107], v[186:187] op_sel_hi:[1,0] neg_lo:[0,1] neg_hi:[0,1]
	v_cndmask_b32_e64 v69, v69, v77, s[0:1]
	v_pk_mul_f32 v[66:67], v[186:187], v[66:67] op_sel:[1,0]
	s_nop 0
	v_pk_fma_f32 v[70:71], v[134:135], v[66:67], v[138:139]
	s_nop 0
	v_cndmask_b32_e64 v66, v78, v70, s[0:1]
	s_nop 1
	v_mov_b32_dpp v84, v66 row_ror:8 row_mask:0xf bank_mask:0xf
	v_cndmask_b32_e64 v66, v79, v71, s[0:1]
	v_cndmask_b32_e64 v70, v70, v84, s[0:1]
	s_nop 0
	v_mov_b32_dpp v85, v66 row_ror:8 row_mask:0xf bank_mask:0xf
	v_cndmask_b32_e64 v66, v84, v78, s[0:1]
	v_cndmask_b32_e64 v67, v85, v79, s[0:1]
	v_cndmask_b32_e64 v71, v71, v85, s[0:1]
	global_store_dwordx4 v[74:75], v[64:67], off offset:128 nt
	global_store_dwordx4 v[72:73], v[68:71], off offset:128 nt
	v_mov_b32_e32 v74, v169
	s_waitcnt lgkmcnt(0)
	v_sub_f32_e32 v64, v112, v188
	v_mul_f32_e32 v64, v189, v64
	v_fma_f32 v66, v156, v64, v144
	v_sub_f32_e32 v64, v113, v188
	v_mul_f32_e32 v64, v189, v64
	v_fma_f32 v67, v157, v64, v145
	v_pk_add_f32 v[64:65], v[116:117], v[188:189] op_sel_hi:[1,0] neg_lo:[0,1] neg_hi:[0,1]
	v_mov_b32_e32 v75, v169
	v_pk_mul_f32 v[64:65], v[188:189], v[64:65] op_sel:[1,0]
	v_add_u32_e32 v72, s48, v205
	v_pk_fma_f32 v[68:69], v[148:149], v[64:65], v[152:153]
	v_ashrrev_i32_e32 v73, 31, v72
	v_cndmask_b32_e64 v64, v66, v68, s[0:1]
	v_mov_b32_e32 v78, v169
	v_mov_b32_e32 v79, v169
	v_mov_b32_dpp v74, v64 row_ror:8 row_mask:0xf bank_mask:0xf
	v_cndmask_b32_e64 v64, v67, v69, s[0:1]
	v_lshlrev_b64 v[72:73], 13, v[72:73]
	v_lshl_add_u64 v[72:73], v[176:177], 0, v[72:73]
	v_mov_b32_dpp v75, v64 row_ror:8 row_mask:0xf bank_mask:0xf
	v_cndmask_b32_e64 v64, v74, v66, s[0:1]
	v_sub_f32_e32 v66, v114, v188
	v_mul_f32_e32 v66, v189, v66
	v_fma_f32 v76, v158, v66, v146
	v_sub_f32_e32 v66, v115, v188
	v_mul_f32_e32 v66, v189, v66
	v_cndmask_b32_e64 v65, v75, v67, s[0:1]
	v_fma_f32 v77, v159, v66, v147
	v_pk_add_f32 v[66:67], v[118:119], v[188:189] op_sel_hi:[1,0] neg_lo:[0,1] neg_hi:[0,1]
	v_cndmask_b32_e64 v69, v69, v75, s[0:1]
	v_pk_mul_f32 v[66:67], v[188:189], v[66:67] op_sel:[1,0]
	v_cndmask_b32_e64 v68, v68, v74, s[0:1]
	v_pk_fma_f32 v[70:71], v[150:151], v[66:67], v[154:155]
	v_lshl_add_u64 v[74:75], v[72:73], 0, v[182:183]
	v_cndmask_b32_e64 v66, v76, v70, s[0:1]
	v_lshl_add_u64 v[72:73], v[72:73], 0, v[168:169]
	s_nop 0
	v_mov_b32_dpp v78, v66 row_ror:8 row_mask:0xf bank_mask:0xf
	v_cndmask_b32_e64 v66, v77, v71, s[0:1]
	v_cndmask_b32_e64 v70, v70, v78, s[0:1]
	s_nop 0
	v_mov_b32_dpp v79, v66 row_ror:8 row_mask:0xf bank_mask:0xf
	v_cndmask_b32_e64 v66, v78, v76, s[0:1]
	v_cndmask_b32_e64 v67, v79, v77, s[0:1]
	global_store_dwordx4 v[74:75], v[64:67], off nt
	v_cndmask_b32_e64 v71, v71, v79, s[0:1]
	global_store_dwordx4 v[72:73], v[68:71], off nt
	v_sub_f32_e32 v64, v80, v188
	v_mul_f32_e32 v64, v189, v64
	v_fma_f32 v66, v140, v64, v128
	v_sub_f32_e32 v64, v81, v188
	v_mul_f32_e32 v64, v189, v64
	v_fma_f32 v67, v141, v64, v129
	v_pk_add_f32 v[64:65], v[88:89], v[188:189] op_sel_hi:[1,0] neg_lo:[0,1] neg_hi:[0,1]
	v_mov_b32_e32 v76, v169
	v_pk_mul_f32 v[64:65], v[188:189], v[64:65] op_sel:[1,0]
	v_mov_b32_e32 v77, v169
	v_pk_fma_f32 v[68:69], v[132:133], v[64:65], v[136:137]
	v_mov_b32_e32 v80, v169
	v_cndmask_b32_e64 v64, v66, v68, s[0:1]
	v_mov_b32_e32 v81, v169
	s_nop 0
	v_mov_b32_dpp v76, v64 row_ror:8 row_mask:0xf bank_mask:0xf
	v_cndmask_b32_e64 v64, v67, v69, s[0:1]
	v_cndmask_b32_e64 v68, v68, v76, s[0:1]
	s_nop 0
	v_mov_b32_dpp v77, v64 row_ror:8 row_mask:0xf bank_mask:0xf
	v_cndmask_b32_e64 v64, v76, v66, s[0:1]
	v_sub_f32_e32 v66, v82, v188
	v_mul_f32_e32 v66, v189, v66
	v_fma_f32 v78, v142, v66, v130
	v_sub_f32_e32 v66, v83, v188
	v_mul_f32_e32 v66, v189, v66
	v_cndmask_b32_e64 v65, v77, v67, s[0:1]
	v_fma_f32 v79, v143, v66, v131
	v_pk_add_f32 v[66:67], v[90:91], v[188:189] op_sel_hi:[1,0] neg_lo:[0,1] neg_hi:[0,1]
	v_cndmask_b32_e64 v69, v69, v77, s[0:1]
	v_pk_mul_f32 v[66:67], v[188:189], v[66:67] op_sel:[1,0]
	v_mov_b32_e32 v76, v169
	v_pk_fma_f32 v[70:71], v[134:135], v[66:67], v[138:139]
	v_mov_b32_e32 v77, v169
	v_cndmask_b32_e64 v66, v78, v70, s[0:1]
	s_nop 1
	v_mov_b32_dpp v80, v66 row_ror:8 row_mask:0xf bank_mask:0xf
	v_cndmask_b32_e64 v66, v79, v71, s[0:1]
	v_cndmask_b32_e64 v70, v70, v80, s[0:1]
	s_nop 0
	v_mov_b32_dpp v81, v66 row_ror:8 row_mask:0xf bank_mask:0xf
	v_cndmask_b32_e64 v66, v80, v78, s[0:1]
	v_cndmask_b32_e64 v67, v81, v79, s[0:1]
	v_cndmask_b32_e64 v71, v71, v81, s[0:1]
	global_store_dwordx4 v[74:75], v[64:67], off offset:128 nt
	global_store_dwordx4 v[72:73], v[68:71], off offset:128 nt
	ds_read_b64 v[64:65], v208
	v_mov_b32_e32 v78, v169
	v_add_u32_e32 v68, s48, v207
	v_ashrrev_i32_e32 v69, 31, v68
	v_mov_b32_e32 v79, v169
	s_waitcnt lgkmcnt(0)
	v_sub_f32_e32 v12, v12, v64
	v_mul_f32_e32 v12, v65, v12
	v_fma_f32 v74, v156, v12, v144
	v_sub_f32_e32 v12, v13, v64
	v_mul_f32_e32 v12, v65, v12
	v_fma_f32 v75, v157, v12, v145
	v_pk_add_f32 v[12:13], v[20:21], v[64:65] op_sel_hi:[1,0] neg_lo:[0,1] neg_hi:[0,1]
	v_sub_f32_e32 v14, v14, v64
	v_pk_mul_f32 v[12:13], v[64:65], v[12:13] op_sel:[1,0]
	v_mul_f32_e32 v14, v65, v14
	v_pk_fma_f32 v[20:21], v[148:149], v[12:13], v[152:153]
	v_lshlrev_b64 v[68:69], 13, v[68:69]
	v_cndmask_b32_e64 v12, v74, v20, s[0:1]
	v_lshl_add_u64 v[68:69], v[176:177], 0, v[68:69]
	v_sub_f32_e32 v0, v0, v64
	v_mov_b32_dpp v76, v12 row_ror:8 row_mask:0xf bank_mask:0xf
	v_cndmask_b32_e64 v12, v75, v21, s[0:1]
	v_mul_f32_e32 v0, v65, v0
	ds_read_b64 v[66:67], v210
	ds_read_b64 v[70:71], v212
	ds_read_b64 v[72:73], v214
	v_mov_b32_dpp v77, v12 row_ror:8 row_mask:0xf bank_mask:0xf
	v_cndmask_b32_e64 v12, v76, v74, s[0:1]
	v_fma_f32 v74, v158, v14, v146
	v_sub_f32_e32 v14, v15, v64
	v_mul_f32_e32 v14, v65, v14
	v_cndmask_b32_e64 v13, v77, v75, s[0:1]
	v_fma_f32 v75, v159, v14, v147
	v_pk_add_f32 v[14:15], v[22:23], v[64:65] op_sel_hi:[1,0] neg_lo:[0,1] neg_hi:[0,1]
	v_cndmask_b32_e64 v21, v21, v77, s[0:1]
	v_pk_mul_f32 v[14:15], v[64:65], v[14:15] op_sel:[1,0]
	v_cndmask_b32_e64 v20, v20, v76, s[0:1]
	v_pk_fma_f32 v[22:23], v[150:151], v[14:15], v[154:155]
	v_sub_f32_e32 v2, v2, v64
	v_cndmask_b32_e64 v14, v74, v22, s[0:1]
	v_mul_f32_e32 v2, v65, v2
	s_nop 0
	v_mov_b32_dpp v78, v14 row_ror:8 row_mask:0xf bank_mask:0xf
	v_cndmask_b32_e64 v14, v75, v23, s[0:1]
	v_cndmask_b32_e64 v22, v22, v78, s[0:1]
	s_nop 0
	v_mov_b32_dpp v79, v14 row_ror:8 row_mask:0xf bank_mask:0xf
	v_cndmask_b32_e64 v14, v78, v74, s[0:1]
	v_cndmask_b32_e64 v15, v79, v75, s[0:1]
	v_lshl_add_u64 v[74:75], v[68:69], 0, v[182:183]
	global_store_dwordx4 v[74:75], v[12:15], off nt
	v_cndmask_b32_e64 v23, v23, v79, s[0:1]
	s_nop 0
	v_fma_f32 v14, v140, v0, v128
	v_sub_f32_e32 v0, v1, v64
	v_mul_f32_e32 v0, v65, v0
	v_fma_f32 v15, v141, v0, v129
	v_pk_add_f32 v[0:1], v[4:5], v[64:65] op_sel_hi:[1,0] neg_lo:[0,1] neg_hi:[0,1]
	v_lshl_add_u64 v[12:13], v[68:69], 0, v[168:169]
	v_pk_mul_f32 v[0:1], v[64:65], v[0:1] op_sel:[1,0]
	global_store_dwordx4 v[12:13], v[20:23], off nt
	v_pk_fma_f32 v[4:5], v[132:133], v[0:1], v[136:137]
	s_nop 0
	v_cndmask_b32_e64 v0, v14, v4, s[0:1]
	v_mov_b32_e32 v20, v169
	v_mov_b32_e32 v21, v169
	v_mov_b32_e32 v22, v169
	v_mov_b32_dpp v20, v0 row_ror:8 row_mask:0xf bank_mask:0xf
	v_cndmask_b32_e64 v0, v15, v5, s[0:1]
	v_mov_b32_e32 v23, v169
	v_cndmask_b32_e64 v4, v4, v20, s[0:1]
	v_mov_b32_dpp v21, v0 row_ror:8 row_mask:0xf bank_mask:0xf
	v_cndmask_b32_e64 v0, v20, v14, s[0:1]
	v_fma_f32 v14, v142, v2, v130
	v_sub_f32_e32 v2, v3, v64
	v_mul_f32_e32 v2, v65, v2
	v_cndmask_b32_e64 v1, v21, v15, s[0:1]
	v_fma_f32 v15, v143, v2, v131
	v_pk_add_f32 v[2:3], v[6:7], v[64:65] op_sel_hi:[1,0] neg_lo:[0,1] neg_hi:[0,1]
	v_cndmask_b32_e64 v5, v5, v21, s[0:1]
	v_pk_mul_f32 v[2:3], v[64:65], v[2:3] op_sel:[1,0]
	s_nop 0
	v_pk_fma_f32 v[6:7], v[134:135], v[2:3], v[138:139]
	s_nop 0
	v_cndmask_b32_e64 v2, v14, v6, s[0:1]
	s_nop 1
	v_mov_b32_dpp v22, v2 row_ror:8 row_mask:0xf bank_mask:0xf
	v_cndmask_b32_e64 v2, v15, v7, s[0:1]
	v_cndmask_b32_e64 v6, v6, v22, s[0:1]
	s_nop 0
	v_mov_b32_dpp v23, v2 row_ror:8 row_mask:0xf bank_mask:0xf
	v_cndmask_b32_e64 v2, v22, v14, s[0:1]
	v_cndmask_b32_e64 v3, v23, v15, s[0:1]
	v_cndmask_b32_e64 v7, v7, v23, s[0:1]
	global_store_dwordx4 v[74:75], v[0:3], off offset:128 nt
	global_store_dwordx4 v[12:13], v[4:7], off offset:128 nt
	v_mov_b32_e32 v14, v169
	s_waitcnt lgkmcnt(2)
	v_sub_f32_e32 v0, v24, v66
	v_mul_f32_e32 v0, v67, v0
	v_fma_f32 v2, v156, v0, v144
	v_sub_f32_e32 v0, v25, v66
	v_mul_f32_e32 v0, v67, v0
	v_fma_f32 v3, v157, v0, v145
	v_pk_add_f32 v[0:1], v[28:29], v[66:67] op_sel_hi:[1,0] neg_lo:[0,1] neg_hi:[0,1]
	v_mov_b32_e32 v15, v169
	v_pk_mul_f32 v[0:1], v[66:67], v[0:1] op_sel:[1,0]
	v_add_u32_e32 v12, s48, v209
	v_pk_fma_f32 v[4:5], v[148:149], v[0:1], v[152:153]
	v_ashrrev_i32_e32 v13, 31, v12
	v_cndmask_b32_e64 v0, v2, v4, s[0:1]
	v_mov_b32_e32 v22, v169
	v_mov_b32_e32 v23, v169
	v_mov_b32_dpp v14, v0 row_ror:8 row_mask:0xf bank_mask:0xf
	v_cndmask_b32_e64 v0, v3, v5, s[0:1]
	v_lshlrev_b64 v[12:13], 13, v[12:13]
	v_lshl_add_u64 v[12:13], v[176:177], 0, v[12:13]
	v_mov_b32_dpp v15, v0 row_ror:8 row_mask:0xf bank_mask:0xf
	v_cndmask_b32_e64 v0, v14, v2, s[0:1]
	v_sub_f32_e32 v2, v26, v66
	v_mul_f32_e32 v2, v67, v2
	v_fma_f32 v20, v158, v2, v146
	v_sub_f32_e32 v2, v27, v66
	v_mul_f32_e32 v2, v67, v2
	v_cndmask_b32_e64 v1, v15, v3, s[0:1]
	v_fma_f32 v21, v159, v2, v147
	v_pk_add_f32 v[2:3], v[30:31], v[66:67] op_sel_hi:[1,0] neg_lo:[0,1] neg_hi:[0,1]
	v_cndmask_b32_e64 v5, v5, v15, s[0:1]
	v_pk_mul_f32 v[2:3], v[66:67], v[2:3] op_sel:[1,0]
	v_cndmask_b32_e64 v4, v4, v14, s[0:1]
	v_pk_fma_f32 v[6:7], v[150:151], v[2:3], v[154:155]
	v_lshl_add_u64 v[14:15], v[12:13], 0, v[182:183]
	v_cndmask_b32_e64 v2, v20, v6, s[0:1]
	v_lshl_add_u64 v[12:13], v[12:13], 0, v[168:169]
	s_nop 0
	v_mov_b32_dpp v22, v2 row_ror:8 row_mask:0xf bank_mask:0xf
	v_cndmask_b32_e64 v2, v21, v7, s[0:1]
	v_cndmask_b32_e64 v6, v6, v22, s[0:1]
	s_nop 0
	v_mov_b32_dpp v23, v2 row_ror:8 row_mask:0xf bank_mask:0xf
	v_cndmask_b32_e64 v2, v22, v20, s[0:1]
	v_cndmask_b32_e64 v3, v23, v21, s[0:1]
	global_store_dwordx4 v[14:15], v[0:3], off nt
	v_cndmask_b32_e64 v7, v7, v23, s[0:1]
	global_store_dwordx4 v[12:13], v[4:7], off nt
	v_sub_f32_e32 v0, v8, v66
	v_mul_f32_e32 v0, v67, v0
	v_fma_f32 v2, v140, v0, v128
	v_sub_f32_e32 v0, v9, v66
	v_mul_f32_e32 v0, v67, v0
	v_fma_f32 v3, v141, v0, v129
	v_pk_add_f32 v[0:1], v[16:17], v[66:67] op_sel_hi:[1,0] neg_lo:[0,1] neg_hi:[0,1]
	v_mov_b32_e32 v8, v169
	v_pk_mul_f32 v[0:1], v[66:67], v[0:1] op_sel:[1,0]
	v_mov_b32_e32 v9, v169
	v_pk_fma_f32 v[4:5], v[132:133], v[0:1], v[136:137]
	v_mov_b32_e32 v16, v169
	v_cndmask_b32_e64 v0, v2, v4, s[0:1]
	v_mov_b32_e32 v17, v169
	s_nop 0
	v_mov_b32_dpp v8, v0 row_ror:8 row_mask:0xf bank_mask:0xf
	v_cndmask_b32_e64 v0, v3, v5, s[0:1]
	v_cndmask_b32_e64 v4, v4, v8, s[0:1]
	s_nop 0
	v_mov_b32_dpp v9, v0 row_ror:8 row_mask:0xf bank_mask:0xf
	v_cndmask_b32_e64 v0, v8, v2, s[0:1]
	v_sub_f32_e32 v2, v10, v66
	v_mul_f32_e32 v2, v67, v2
	v_fma_f32 v10, v142, v2, v130
	v_sub_f32_e32 v2, v11, v66
	v_mul_f32_e32 v2, v67, v2
	v_cndmask_b32_e64 v1, v9, v3, s[0:1]
	v_fma_f32 v11, v143, v2, v131
	v_pk_add_f32 v[2:3], v[18:19], v[66:67] op_sel_hi:[1,0] neg_lo:[0,1] neg_hi:[0,1]
	v_cndmask_b32_e64 v5, v5, v9, s[0:1]
	v_pk_mul_f32 v[2:3], v[66:67], v[2:3] op_sel:[1,0]
	v_add_u32_e32 v8, s48, v211
	v_pk_fma_f32 v[6:7], v[134:135], v[2:3], v[138:139]
	v_ashrrev_i32_e32 v9, 31, v8
	v_cndmask_b32_e64 v2, v10, v6, s[0:1]
	v_lshlrev_b64 v[8:9], 13, v[8:9]
	v_lshl_add_u64 v[8:9], v[176:177], 0, v[8:9]
	v_mov_b32_dpp v16, v2 row_ror:8 row_mask:0xf bank_mask:0xf
	v_cndmask_b32_e64 v2, v11, v7, s[0:1]
	v_cndmask_b32_e64 v6, v6, v16, s[0:1]
	s_nop 0
	v_mov_b32_dpp v17, v2 row_ror:8 row_mask:0xf bank_mask:0xf
	v_cndmask_b32_e64 v2, v16, v10, s[0:1]
	v_cndmask_b32_e64 v3, v17, v11, s[0:1]
	v_cndmask_b32_e64 v7, v7, v17, s[0:1]
	global_store_dwordx4 v[14:15], v[0:3], off offset:128 nt
	global_store_dwordx4 v[12:13], v[4:7], off offset:128 nt
	v_mov_b32_e32 v10, v169
	s_waitcnt lgkmcnt(1)
	v_sub_f32_e32 v0, v40, v70
	v_mul_f32_e32 v0, v71, v0
	v_fma_f32 v2, v156, v0, v144
	v_sub_f32_e32 v0, v41, v70
	v_mul_f32_e32 v0, v71, v0
	v_fma_f32 v3, v157, v0, v145
	v_pk_add_f32 v[0:1], v[44:45], v[70:71] op_sel_hi:[1,0] neg_lo:[0,1] neg_hi:[0,1]
	v_mov_b32_e32 v11, v169
	v_pk_mul_f32 v[0:1], v[70:71], v[0:1] op_sel:[1,0]
	v_mov_b32_e32 v14, v169
	v_pk_fma_f32 v[4:5], v[148:149], v[0:1], v[152:153]
	v_mov_b32_e32 v15, v169
	v_cndmask_b32_e64 v0, v2, v4, s[0:1]
	v_mov_b32_e32 v16, v169
	v_mov_b32_e32 v17, v169
	v_mov_b32_dpp v10, v0 row_ror:8 row_mask:0xf bank_mask:0xf
	v_cndmask_b32_e64 v0, v3, v5, s[0:1]
	v_cndmask_b32_e64 v4, v4, v10, s[0:1]
	s_nop 0
	v_mov_b32_dpp v11, v0 row_ror:8 row_mask:0xf bank_mask:0xf
	v_cndmask_b32_e64 v0, v10, v2, s[0:1]
	v_sub_f32_e32 v2, v42, v70
	v_mul_f32_e32 v2, v71, v2
	v_fma_f32 v12, v158, v2, v146
	v_sub_f32_e32 v2, v43, v70
	v_mul_f32_e32 v2, v71, v2
	v_cndmask_b32_e64 v1, v11, v3, s[0:1]
	v_fma_f32 v13, v159, v2, v147
	v_pk_add_f32 v[2:3], v[46:47], v[70:71] op_sel_hi:[1,0] neg_lo:[0,1] neg_hi:[0,1]
	v_cndmask_b32_e64 v5, v5, v11, s[0:1]
	v_pk_mul_f32 v[2:3], v[70:71], v[2:3] op_sel:[1,0]
	v_lshl_add_u64 v[10:11], v[8:9], 0, v[182:183]
	v_pk_fma_f32 v[6:7], v[150:151], v[2:3], v[154:155]
	v_lshl_add_u64 v[8:9], v[8:9], 0, v[168:169]
	v_cndmask_b32_e64 v2, v12, v6, s[0:1]
	s_nop 1
	v_mov_b32_dpp v14, v2 row_ror:8 row_mask:0xf bank_mask:0xf
	v_cndmask_b32_e64 v2, v13, v7, s[0:1]
	v_cndmask_b32_e64 v6, v6, v14, s[0:1]
	s_nop 0
	v_mov_b32_dpp v15, v2 row_ror:8 row_mask:0xf bank_mask:0xf
	v_cndmask_b32_e64 v2, v14, v12, s[0:1]
	v_cndmask_b32_e64 v3, v15, v13, s[0:1]
	global_store_dwordx4 v[10:11], v[0:3], off nt
	v_cndmask_b32_e64 v7, v7, v15, s[0:1]
	global_store_dwordx4 v[8:9], v[4:7], off nt
	v_sub_f32_e32 v0, v32, v70
	v_mul_f32_e32 v0, v71, v0
	v_fma_f32 v2, v140, v0, v128
	v_sub_f32_e32 v0, v33, v70
	v_mul_f32_e32 v0, v71, v0
	v_fma_f32 v3, v141, v0, v129
	v_pk_add_f32 v[0:1], v[36:37], v[70:71] op_sel_hi:[1,0] neg_lo:[0,1] neg_hi:[0,1]
	v_mov_b32_e32 v12, v169
	v_pk_mul_f32 v[0:1], v[70:71], v[0:1] op_sel:[1,0]
	v_mov_b32_e32 v13, v169
	v_pk_fma_f32 v[4:5], v[132:133], v[0:1], v[136:137]
	s_nop 0
	v_cndmask_b32_e64 v0, v2, v4, s[0:1]
	s_nop 1
	v_mov_b32_dpp v12, v0 row_ror:8 row_mask:0xf bank_mask:0xf
	v_cndmask_b32_e64 v0, v3, v5, s[0:1]
	v_cndmask_b32_e64 v4, v4, v12, s[0:1]
	s_nop 0
	v_mov_b32_dpp v13, v0 row_ror:8 row_mask:0xf bank_mask:0xf
	v_cndmask_b32_e64 v0, v12, v2, s[0:1]
	v_sub_f32_e32 v2, v34, v70
	v_mul_f32_e32 v2, v71, v2
	v_fma_f32 v14, v142, v2, v130
	v_sub_f32_e32 v2, v35, v70
	v_mul_f32_e32 v2, v71, v2
	v_cndmask_b32_e64 v1, v13, v3, s[0:1]
	v_fma_f32 v15, v143, v2, v131
	v_pk_add_f32 v[2:3], v[38:39], v[70:71] op_sel_hi:[1,0] neg_lo:[0,1] neg_hi:[0,1]
	v_cndmask_b32_e64 v5, v5, v13, s[0:1]
	v_pk_mul_f32 v[2:3], v[70:71], v[2:3] op_sel:[1,0]
	v_mov_b32_e32 v13, v169
	v_pk_fma_f32 v[6:7], v[134:135], v[2:3], v[138:139]
	s_nop 0
	v_cndmask_b32_e64 v2, v14, v6, s[0:1]
	s_nop 1
	v_mov_b32_dpp v16, v2 row_ror:8 row_mask:0xf bank_mask:0xf
	v_cndmask_b32_e64 v2, v15, v7, s[0:1]
	v_cndmask_b32_e64 v6, v6, v16, s[0:1]
	s_nop 0
	v_mov_b32_dpp v17, v2 row_ror:8 row_mask:0xf bank_mask:0xf
	v_cndmask_b32_e64 v2, v16, v14, s[0:1]
	v_cndmask_b32_e64 v3, v17, v15, s[0:1]
	v_cndmask_b32_e64 v7, v7, v17, s[0:1]
	global_store_dwordx4 v[10:11], v[0:3], off offset:128 nt
	global_store_dwordx4 v[8:9], v[4:7], off offset:128 nt
	v_mov_b32_e32 v10, v169
	s_waitcnt lgkmcnt(0)
	v_sub_f32_e32 v0, v48, v72
	v_mul_f32_e32 v0, v73, v0
	v_fma_f32 v2, v156, v0, v144
	v_sub_f32_e32 v0, v49, v72
	v_mul_f32_e32 v0, v73, v0
	v_fma_f32 v3, v157, v0, v145
	v_pk_add_f32 v[0:1], v[52:53], v[72:73] op_sel_hi:[1,0] neg_lo:[0,1] neg_hi:[0,1]
	v_mov_b32_e32 v11, v169
	v_pk_mul_f32 v[0:1], v[72:73], v[0:1] op_sel:[1,0]
	v_add_u32_e32 v8, s48, v213
	v_pk_fma_f32 v[4:5], v[148:149], v[0:1], v[152:153]
	v_ashrrev_i32_e32 v9, 31, v8
	v_cndmask_b32_e64 v0, v2, v4, s[0:1]
	v_mov_b32_e32 v14, v169
	v_lshlrev_b64 v[8:9], 13, v[8:9]
	v_mov_b32_dpp v10, v0 row_ror:8 row_mask:0xf bank_mask:0xf
	v_cndmask_b32_e64 v0, v3, v5, s[0:1]
	v_lshl_add_u64 v[8:9], v[176:177], 0, v[8:9]
	v_cndmask_b32_e64 v4, v4, v10, s[0:1]
	v_mov_b32_dpp v11, v0 row_ror:8 row_mask:0xf bank_mask:0xf
	v_cndmask_b32_e64 v0, v10, v2, s[0:1]
	v_sub_f32_e32 v2, v50, v72
	v_mul_f32_e32 v2, v73, v2
	v_fma_f32 v12, v158, v2, v146
	v_sub_f32_e32 v2, v51, v72
	v_mul_f32_e32 v2, v73, v2
	v_cndmask_b32_e64 v1, v11, v3, s[0:1]
	v_fmac_f32_e32 v147, v159, v2
	v_pk_add_f32 v[2:3], v[54:55], v[72:73] op_sel_hi:[1,0] neg_lo:[0,1] neg_hi:[0,1]
	v_cndmask_b32_e64 v5, v5, v11, s[0:1]
	v_pk_mul_f32 v[2:3], v[72:73], v[2:3] op_sel:[1,0]
	v_lshl_add_u64 v[10:11], v[8:9], 0, v[182:183]
	v_pk_fma_f32 v[6:7], v[150:151], v[2:3], v[154:155]
	v_lshl_add_u64 v[8:9], v[8:9], 0, v[168:169]
	v_cndmask_b32_e64 v2, v12, v6, s[0:1]
	v_mov_b32_e32 v15, v169
	v_mov_b32_e32 v16, v169
	v_mov_b32_dpp v13, v2 row_ror:8 row_mask:0xf bank_mask:0xf
	v_cndmask_b32_e64 v2, v147, v7, s[0:1]
	v_cndmask_b32_e64 v6, v6, v13, s[0:1]
	s_nop 0
	v_mov_b32_dpp v14, v2 row_ror:8 row_mask:0xf bank_mask:0xf
	v_cndmask_b32_e64 v2, v13, v12, s[0:1]
	v_cndmask_b32_e64 v3, v14, v147, s[0:1]
	global_store_dwordx4 v[10:11], v[0:3], off nt
	v_cndmask_b32_e64 v7, v7, v14, s[0:1]
	global_store_dwordx4 v[8:9], v[4:7], off nt
	v_sub_f32_e32 v0, v56, v72
	v_mul_f32_e32 v0, v73, v0
	v_fma_f32 v2, v140, v0, v128
	v_sub_f32_e32 v0, v57, v72
	v_mul_f32_e32 v0, v73, v0
	v_fma_f32 v3, v141, v0, v129
	v_pk_add_f32 v[0:1], v[60:61], v[72:73] op_sel_hi:[1,0] neg_lo:[0,1] neg_hi:[0,1]
	v_mov_b32_e32 v12, v169
	v_pk_mul_f32 v[0:1], v[72:73], v[0:1] op_sel:[1,0]
	v_mov_b32_e32 v13, v169
	v_pk_fma_f32 v[4:5], v[132:133], v[0:1], v[136:137]
	s_nop 0
	v_cndmask_b32_e64 v0, v2, v4, s[0:1]
	s_nop 1
	v_mov_b32_dpp v12, v0 row_ror:8 row_mask:0xf bank_mask:0xf
	v_cndmask_b32_e64 v0, v3, v5, s[0:1]
	v_cndmask_b32_e64 v4, v4, v12, s[0:1]
	s_nop 0
	v_mov_b32_dpp v13, v0 row_ror:8 row_mask:0xf bank_mask:0xf
	v_cndmask_b32_e64 v0, v12, v2, s[0:1]
	v_sub_f32_e32 v2, v58, v72
	v_mul_f32_e32 v2, v73, v2
	v_fma_f32 v14, v142, v2, v130
	v_sub_f32_e32 v2, v59, v72
	v_mul_f32_e32 v2, v73, v2
	v_cndmask_b32_e64 v1, v13, v3, s[0:1]
	v_fmac_f32_e32 v131, v143, v2
	v_pk_add_f32 v[2:3], v[62:63], v[72:73] op_sel_hi:[1,0] neg_lo:[0,1] neg_hi:[0,1]
	v_cndmask_b32_e64 v5, v5, v13, s[0:1]
	v_pk_mul_f32 v[2:3], v[72:73], v[2:3] op_sel:[1,0]
	s_nop 0
	v_pk_fma_f32 v[6:7], v[134:135], v[2:3], v[138:139]
	s_nop 0
	v_cndmask_b32_e64 v2, v14, v6, s[0:1]
	s_nop 1
	v_mov_b32_dpp v15, v2 row_ror:8 row_mask:0xf bank_mask:0xf
	v_cndmask_b32_e64 v2, v131, v7, s[0:1]
	v_cndmask_b32_e64 v6, v6, v15, s[0:1]
	s_nop 0
	v_mov_b32_dpp v16, v2 row_ror:8 row_mask:0xf bank_mask:0xf
	v_cndmask_b32_e64 v2, v15, v14, s[0:1]
	v_cndmask_b32_e64 v3, v16, v131, s[0:1]
	v_cndmask_b32_e64 v7, v7, v16, s[0:1]
	global_store_dwordx4 v[10:11], v[0:3], off offset:128 nt
	global_store_dwordx4 v[8:9], v[4:7], off offset:128 nt
	s_cbranch_vccnz .LBB0_495
	s_andn2_b64 vcc, exec, s[20:21]
	s_cbranch_vccnz .LBB0_494
	s_barrier
	s_branch .LBB0_494
